# L2 touch of the first sample-attention unit's cache K/V block during the GLU sample-row unit (on top of local seams + barrier-shadow prefetch)
# speedup vs baseline: 1.0064x; 1.0027x over previous
; __device__ __forceinline__ int opq(int v) { asm volatile("" : "+v"(v)); return v; }
;     __device__ __forceinline__ void prefetch4(int row, int col, Pre& p) const { p.gw = *(const u32x2*)(Zg + (size_t)row * INC + col); if (SECOND) p.pw = *(const u32x2*)(O + (size_t)row * DM + col); }
; template <int CT, class Epi> __device__ __forceinline__ void skinny_gemm(LAS unsigned char* lds, const bf16_t* A, const bf16_t* Bt, int N, int K, const Epi& E, int first) {
;     ...
;     for (int u = (int)((blockIdx.x + G - first % G) % G); u < nunits; u += G) {
;         const int mt = u & 7, nt = u >> 3;
;         const bf16_t* ap = A + (size_t)(NTOK_P + mt * 64 + r) * K + wave * kw + 8 * qd;
;         const bf16_t* bp = Bt + (size_t)(nt * 16 * CT + r) * K + wave * kw + 8 * qd;
;         typename Epi::Pre pre[CT / 2];
; #pragma unroll
;         for (int e = 0; e < CT / 2; ++e) { const int idx = tid + e * 512; E.prefetch4(NTOK_P + mt * 64 + idx / (4 * CT), nt * 16 * CT + (idx % (4 * CT)) * 4, pre[e]); }
;         f32x4 acc[4][CT];
; #pragma unroll
;         for (int rt = 0; rt < 4; ++rt)
; #pragma unroll
;             for (int ct = 0; ct < CT; ++ct) acc[rt][ct] = (f32x4){0.f, 0.f, 0.f, 0.f};
; __global__ void __launch_bounds__(512, 2) mk_fwd(Args a) {
;     ...
;         { int u0 = -1, un = 0, us = 1;
;           if (G == 256) { if (bx >= 192) { u0 = bx - 192; un = 2; us = 64; } else if (bx < 128) { u0 = 128 + bx; un = 1; } }
;           else { u0 = bx; un = (2 * DEC_B - bx + G - 1) / G; us = G; }
;           for (int k = 0; k < un; ++k) { const int u = u0 + k * us; attn_sample_unit(a, lds, l, u >> 1, u & 1, opq(threadIdx.x)); } }
.LBB0_590:
	s_and_b32 s7, s0, 0x1c0
	s_bitset1_b32 s7, 14
	v_or_b32_e32 v0, s7, v22
	v_lshlrev_b32_e32 v0, 10, v0
	s_and_b32 s10, s1, 0xffffffe0
	v_lshl_add_u64 v[36:37], v[2:3], 0, v[0:1]
	v_or_b32_e32 v28, s10, v22
	v_add_co_u32_e32 v44, vcc, s84, v36
	v_ashrrev_i32_e32 v29, 31, v28
	s_nop 0
	v_addc_co_u32_e32 v45, vcc, 0, v37, vcc
	v_lshlrev_b64 v[32:33], 10, v[28:29]
	v_add_u32_e32 v28, s7, v23
	v_add_co_u32_e32 v52, vcc, s85, v36
	s_and_b32 s7, s6, 0x3ffffff8
	v_ashrrev_i32_e32 v29, 31, v28
	v_addc_co_u32_e32 v53, vcc, 0, v37, vcc
	v_add_lshl_u32 v30, s7, v24, 2
	v_lshlrev_b64 v[92:93], 10, v[28:29]
	v_add_co_u32_e32 v60, vcc, s72, v36
	v_lshl_add_u64 v[28:29], s[40:41], 0, v[92:93]
	v_ashrrev_i32_e32 v31, 31, v30
	s_waitcnt vmcnt(2)
	v_lshl_add_u64 v[68:69], v[20:21], 0, v[32:33]
	v_addc_co_u32_e32 v61, vcc, 0, v37, vcc
	v_lshl_add_u64 v[28:29], v[30:31], 1, v[28:29]
	v_add_co_u32_e32 v76, vcc, s84, v68
	global_load_dwordx2 v[94:95], v[28:29], off
	v_lshl_add_u64 v[28:29], v[30:31], 2, s[8:9]
	v_addc_co_u32_e32 v77, vcc, 0, v69, vcc
	global_load_dwordx4 v[28:31], v[28:29], off
	s_nop 0
	s_mov_b32 s100, 0x2000
	s_mov_b32 s101, 0
	v_readfirstlane_b32 s98, v184
	v_and_b32_e32 v246, 63, v184
	s_nop 1
	s_lshr_b32 s98, s98, 6
	s_lshl_b32 s99, s98, 12
	s_add_i32 s99, s99, 0x10000
	s_lshl_b32 s98, s98, 13
	v_and_b32_e32 v247, 15, v246
	v_lshrrev_b32_e32 v248, 4, v246
	v_lshrrev_b32_e32 v249, 3, v246
	v_and_b32_e32 v246, 7, v246
	v_xor_b32_e32 v246, v246, v249
	v_sub_u32_e32 v249, v249, v247
	v_sub_u32_e32 v246, v246, v248
	v_lshlrev_b32_e32 v249, 10, v249
	v_lshl_add_u32 v240, v246, 4, v249
	v_ashrrev_i32_e32 v241, 31, v240
	v_and_b32_e32 v246, 7, v247
	v_xor_b32_e32 v246, v246, v248
	v_lshlrev_b32_e32 v246, 4, v246
	v_lshl_add_u32 v246, v247, 7, v246
	v_add_u32_e32 v242, s98, v246
	v_xor_b32_e32 v243, 64, v242
	v_add_u32_e32 v244, s99, v246
	v_xor_b32_e32 v245, 64, v244
	s_mov_b32 m0, s98
	v_lshl_add_u64 v[236:237], v[36:37], 0, v[240:241]
	global_load_lds_dwordx4 v[236:237], off
	s_add_i32 m0, s98, 0x400
	v_lshl_add_u64 v[236:237], v[236:237], 0, s[100:101]
	global_load_lds_dwordx4 v[236:237], off
	s_add_i32 m0, s98, 0x800
	v_lshl_add_u64 v[236:237], v[236:237], 0, s[100:101]
	global_load_lds_dwordx4 v[236:237], off
	s_add_i32 m0, s98, 0xc00
	v_lshl_add_u64 v[236:237], v[236:237], 0, s[100:101]
	global_load_lds_dwordx4 v[236:237], off
	s_add_i32 m0, s98, 0x1000
	v_lshl_add_u64 v[236:237], v[236:237], 0, s[100:101]
	global_load_lds_dwordx4 v[236:237], off
	s_add_i32 m0, s98, 0x1400
	v_lshl_add_u64 v[236:237], v[236:237], 0, s[100:101]
	global_load_lds_dwordx4 v[236:237], off
	s_add_i32 m0, s98, 0x1800
	v_lshl_add_u64 v[236:237], v[236:237], 0, s[100:101]
	global_load_lds_dwordx4 v[236:237], off
	s_add_i32 m0, s98, 0x1c00
	v_lshl_add_u64 v[236:237], v[236:237], 0, s[100:101]
	global_load_lds_dwordx4 v[236:237], off
	s_mov_b32 m0, s99
	v_lshl_add_u64 v[238:239], v[68:69], 0, v[240:241]
	global_load_lds_dwordx4 v[238:239], off
	s_add_i32 m0, s99, 0x400
	v_lshl_add_u64 v[238:239], v[238:239], 0, s[100:101]
	global_load_lds_dwordx4 v[238:239], off
	s_add_i32 m0, s99, 0x800
	v_lshl_add_u64 v[238:239], v[238:239], 0, s[100:101]
	global_load_lds_dwordx4 v[238:239], off
	s_add_i32 m0, s99, 0xc00
	v_lshl_add_u64 v[238:239], v[238:239], 0, s[100:101]
	global_load_lds_dwordx4 v[238:239], off
	s_waitcnt vmcnt(0)
	ds_read_b128 v[32:35], v242
	ds_read_b128 v[40:43], v242 offset:2048
	ds_read_b128 v[48:51], v242 offset:4096
	ds_read_b128 v[56:59], v242 offset:6144
	ds_read_b128 v[36:39], v243
	ds_read_b128 v[44:47], v243 offset:2048
	ds_read_b128 v[52:55], v243 offset:4096
	ds_read_b128 v[60:63], v243 offset:6144
	ds_read_b128 v[64:67], v244
	ds_read_b128 v[72:75], v244 offset:2048
	ds_read_b128 v[68:71], v245
	ds_read_b128 v[76:79], v245 offset:2048
	s_waitcnt lgkmcnt(0)
	s_nop 0
	s_nop 0
	s_nop 0
	s_nop 0
	s_nop 0
	s_nop 0
	s_nop 0
	s_nop 0
	s_nop 0
	s_nop 0
	s_nop 0
	v_readlane_b32 s99, v254, 11
	v_readlane_b32 s98, v254, 10
	s_cmp_lt_i32 s99, 1
	s_cbranch_scc1 .Lsp_skip
	s_and_b32 s98, s98, 0xff
	v_readlane_b32 s101, v255, 41
	s_lshr_b32 s100, s98, 1
	s_and_b32 s98, s98, 1
	s_lshl_b32 s101, s101, 7
	s_add_i32 s100, s100, s101
	s_lshl_b32 s98, s98, 8
	s_lshl_b32 s100, s100, 16
	s_add_i32 s100, s100, s98
	v_and_b32_e32 v116, 0xff, v184
	v_lshrrev_b32_e32 v117, 1, v116
	v_and_b32_e32 v116, 1, v116
	v_lshlrev_b32_e32 v117, 9, v117
	v_lshl_add_u32 v116, v116, 7, v117
	v_add_u32_e32 v116, s100, v116
	v_mov_b32_e32 v117, 0
	v_mov_b32_e32 v118, s54
	v_mov_b32_e32 v119, s55
	v_mov_b32_e32 v120, s52
	v_mov_b32_e32 v121, s53
	v_cmp_gt_u32_e32 vcc, 0x100, v184
	v_cndmask_b32_e32 v118, v118, v120, vcc
	v_cndmask_b32_e32 v119, v119, v121, vcc
	v_lshl_add_u64 v[118:119], v[118:119], 0, v[116:117]
	global_load_dword v116, v[118:119], off
; #define LAS __attribute__((address_space(3)))
; __device__ __forceinline__ float bflo(unsigned w) { return __uint_as_float(w << 16); }
; __device__ __forceinline__ float bfhi(unsigned w) { return __uint_as_float(w & 0xffff0000u); }
; __device__ __forceinline__ unsigned pk2(float lo, float hi) { return pg8::cvt_pk_bf16(lo, hi); }
; __device__ __forceinline__ float sigm(float x) { return __builtin_amdgcn_rcpf(1.f + __builtin_amdgcn_exp2f(-LOG2E * x)); }
;     __device__ __forceinline__ void apply4(int row, int col, f32x4 v, const Pre& p) const {
;         const u32x2 yw = p.yw; const f32x4 bb = p.bb;
;         u32x2 w; w.x = pk2(bflo(yw.x) * sigm(v[0] + bb[0]), bfhi(yw.x) * sigm(v[1] + bb[1])); w.y = pk2(bflo(yw.y) * sigm(v[2] + bb[2]), bfhi(yw.y) * sigm(v[3] + bb[3]));
;         *(u32x2*)(O + (size_t)row * 512 + col) = w;
; template <int CT, class Epi> __device__ __forceinline__ void skinny_gemm(LAS unsigned char* lds, const bf16_t* A, const bf16_t* Bt, int N, int K, const Epi& E, int first) {
;     ...
;         if (nsteps >= 4) {
; #pragma unroll 1
;             for (int s0 = 0; s0 < nsteps; s0 += 4) SKINNY_GROUP(4, s0);
;         } else SKINNY_GROUP(2, 0);
;     ...
; #pragma unroll
;         for (int rt = 0; rt < 4; ++rt)
; #pragma unroll
;             for (int ct = 0; ct < CT; ++ct) *(LAS f32x4*)(red + wave * (64 * 16 * CT) + (rt * 16 + r) * (16 * CT) + ct * 16 + 4 * qd) = acc[rt][ct];
;         __syncthreads();
; #pragma unroll
;         for (int e = 0; e < CT / 2; ++e) { const int idx = tid + e * 512, row = idx / (4 * CT), c4 = idx % (4 * CT);
;             f32x4 v = *(const LAS f32x4*)(red + row * (16 * CT) + c4 * 4);
; #pragma unroll
;             for (int w = 1; w < 8; ++w) v = v + *(const LAS f32x4*)(red + w * (64 * 16 * CT) + row * (16 * CT) + c4 * 4);
;             E.apply4(NTOK_P + mt * 64 + row, nt * 16 * CT + c4 * 4, v, pre[e]); }
;         __syncthreads();
.Lsp_skip:
	v_mfma_f32_16x16x32_bf16 v[80:83], v[64:67], v[32:35], 0
	v_mfma_f32_16x16x32_bf16 v[32:35], v[72:75], v[32:35], 0
	v_mfma_f32_16x16x32_bf16 v[84:87], v[64:67], v[40:43], 0
	v_mfma_f32_16x16x32_bf16 v[40:43], v[72:75], v[40:43], 0
	v_mfma_f32_16x16x32_bf16 v[88:91], v[64:67], v[48:51], 0
	v_mfma_f32_16x16x32_bf16 v[48:51], v[72:75], v[48:51], 0
	v_mfma_f32_16x16x32_bf16 v[64:67], v[64:67], v[56:59], 0
	v_mfma_f32_16x16x32_bf16 v[56:59], v[72:75], v[56:59], 0
	v_mfma_f32_16x16x32_bf16 v[72:75], v[68:71], v[36:39], v[80:83]
	v_mfma_f32_16x16x32_bf16 v[32:35], v[76:79], v[36:39], v[32:35]
	v_mfma_f32_16x16x32_bf16 v[36:39], v[68:71], v[44:47], v[84:87]
	v_mfma_f32_16x16x32_bf16 v[40:43], v[76:79], v[44:47], v[40:43]
	v_mfma_f32_16x16x32_bf16 v[44:47], v[68:71], v[52:55], v[88:91]
	v_mfma_f32_16x16x32_bf16 v[48:51], v[76:79], v[52:55], v[48:51]
	v_mfma_f32_16x16x32_bf16 v[52:55], v[68:71], v[60:63], v[64:67]
	v_mfma_f32_16x16x32_bf16 v[56:59], v[76:79], v[60:63], v[56:59]
	ds_write_b128 v27, v[72:75]
	s_nop 0
	ds_write_b128 v27, v[32:35] offset:64
	ds_write_b128 v27, v[36:39] offset:2048
	ds_write_b128 v27, v[40:43] offset:2112
	ds_write_b128 v27, v[44:47] offset:4096
	ds_write_b128 v27, v[48:51] offset:4160
	ds_write_b128 v27, v[52:55] offset:6144
	ds_write_b128 v27, v[56:59] offset:6208
	s_waitcnt lgkmcnt(0)
	s_barrier
	ds_read_b128 v[32:35], v26
	ds_read_b128 v[36:39], v26 offset:8192
	ds_read_b128 v[40:43], v26 offset:16384
	ds_read_b128 v[44:47], v26 offset:24576
	v_lshlrev_b32_e32 v0, 16, v94
	v_and_b32_e32 v52, 0xffff0000, v94
	s_waitcnt lgkmcnt(2)
	v_pk_add_f32 v[34:35], v[34:35], v[38:39]
	v_pk_add_f32 v[32:33], v[32:33], v[36:37]
	s_waitcnt lgkmcnt(1)
	v_pk_add_f32 v[34:35], v[34:35], v[42:43]
	v_pk_add_f32 v[36:37], v[32:33], v[40:41]
	s_waitcnt lgkmcnt(0)
	v_pk_add_f32 v[48:49], v[34:35], v[46:47]
	ds_read_b128 v[32:35], v26 offset:32768
	v_pk_add_f32 v[50:51], v[36:37], v[44:45]
	ds_read_b128 v[36:39], v26 offset:40960
	ds_read_b128 v[40:43], v26 offset:49152
	ds_read_b128 v[44:47], v26 offset:57344
	v_lshlrev_b32_e32 v53, 16, v95
	v_and_b32_e32 v54, 0xffff0000, v95
	s_waitcnt lgkmcnt(3)
	v_pk_add_f32 v[32:33], v[50:51], v[32:33]
	v_pk_add_f32 v[34:35], v[48:49], v[34:35]
	s_waitcnt lgkmcnt(2)
	v_pk_add_f32 v[32:33], v[32:33], v[36:37]
	v_pk_add_f32 v[34:35], v[34:35], v[38:39]
	s_waitcnt lgkmcnt(1)
	v_pk_add_f32 v[32:33], v[32:33], v[40:41]
	v_pk_add_f32 v[34:35], v[34:35], v[42:43]
	s_waitcnt lgkmcnt(0)
	v_pk_add_f32 v[32:33], v[32:33], v[44:45]
	v_pk_add_f32 v[34:35], v[34:35], v[46:47]
	v_add_f32_e32 v28, v28, v32
	v_mul_f32_e32 v28, 0xbfb8aa3b, v28
	v_exp_f32_e32 v28, v28
	v_add_f32_e32 v30, v30, v34
	v_mul_f32_e32 v30, 0xbfb8aa3b, v30
	v_add_f32_e32 v31, v31, v35
	v_add_f32_e32 v28, 1.0, v28
	v_rcp_f32_e32 v32, v28
	v_add_f32_e32 v28, v29, v33
	v_mul_f32_e32 v28, 0xbfb8aa3b, v28
	v_exp_f32_e32 v33, v28
	v_exp_f32_e32 v30, v30
	v_mul_f32_e32 v31, 0xbfb8aa3b, v31
	v_exp_f32_e32 v31, v31
	v_mul_f32_e32 v0, v32, v0
	v_add_f32_e32 v32, 1.0, v33
	v_rcp_f32_e32 v32, v32
	v_add_f32_e32 v30, 1.0, v30
	v_rcp_f32_e32 v33, v30
	v_add_f32_e32 v30, 1.0, v31
	v_rcp_f32_e32 v31, v30
	v_add_u32_e32 v28, s10, v25
	v_mul_f32_e32 v30, v32, v52
	v_ashrrev_i32_e32 v29, 31, v28
	v_cvt_pk_bf16_f32 v30, v0, v30
	v_mul_f32_e32 v0, v33, v53
	v_lshl_add_u64 v[32:33], s[50:51], 0, v[92:93]
	s_add_i32 s6, s6, s34
	s_add_i32 s1, s1, s83
	s_add_i32 s0, s0, s82
	v_mul_f32_e32 v31, v31, v54
	v_lshl_add_u64 v[28:29], v[28:29], 1, v[32:33]
	s_cmpk_lt_i32 s6, 0x80
	v_cvt_pk_bf16_f32 v31, v0, v31
	global_store_dwordx2 v[28:29], v[30:31], off
	s_barrier
	s_cbranch_scc1 .LBB0_590
